# out-projection K-loop: A-fragment LDS read address adds folded into ds_read offsets; no VALU address arithmetic left in any GEMM K-loop
# baseline (speedup 1.0000x reference)
; #define PG8_STAGE(bufoff, gbase, voff) do { _Pragma("unroll") for (int _i = 0; _i < 2; ++_i) \
;         __builtin_amdgcn_global_load_lds((const unsigned*)((const char*)(gbase) + (voff)[_i]), (PG8_LAS unsigned*)(lds + (bufoff) + ldsw + _i * 8192), 16, 0, 0); } while (0)
; #define PG8_WAIT_V(n) asm volatile("s_waitcnt vmcnt(" #n ")" ::: "memory")
; #define PG8_BAR __builtin_amdgcn_s_barrier()
; template <class Epi, class Sched, bool ALIGN_EPI = false, bool SP2 = false>
; __device__ __forceinline__ void gemm_phase(PG8_LAS unsigned char* lds, const Gemm g, const Sched& S, const Epi& E) {
;     ...
;     for (int i = 0; i < 2; ++i) { int R, C; stage_rc(tid * 16 + i * 8192, R, C); const int Rb = Epi::PERM ? ((R & ~31) + perm32(R & 31)) : R;
;         voffA[i] = (unsigned)(R * K + C) * 2u; voffB[i] = (unsigned)(Rb * K + C) * 2u; }
;     const size_t kstep = (size_t)(BK * 2);
;     const size_t hstep = (size_t)HALF * K * 2;
;     const size_t tstep = 2 * hstep;
;     const unsigned ldsw = (unsigned)wid * 1024u;
;     const int aoff = lds_byte(wr * 64 + fr, fq * 8), boff = lds_byte(wc * 32 + fr, fq * 8);
;     ...
;     Unit cur, nxt; int ui = 0;
;     if (!S.next(0, cur)) return;
;     f32x4 acc[2][2][4][2];
; #pragma unroll
;     for (int a = 0; a < 2; ++a)
; #pragma unroll
;         for (int b = 0; b < 2; ++b)
; #pragma unroll
;             for (int m = 0; m < 4; ++m)
; #pragma unroll
;                 for (int n = 0; n < 2; ++n) acc[a][b][m][n] = (f32x4){0.f, 0.f, 0.f, 0.f};
;     bf16x8 At[4][2], B0[2][2], B1[2][2];
;     const char* cA = (const char*)g.A + (size_t)cur.pm * tstep; const char* cB = (const char*)g.Bt + (size_t)cur.pn * tstep;
;     S.a_ready(cur);
;     if constexpr (SP2) {
;         PG8_STAGE(PG8_SB(0, 0), cB, voffB); PG8_STAGE(PG8_SB(0, 1), cB + hstep, voffB); PG8_STAGE(PG8_SA(0, 0), cA, voffA); PG8_STAGE(PG8_SA(0, 1), cA + hstep, voffA);
;         if (wr == 1) PG8_BAR;
;         PG8_WAIT_V(2); PG8_BAR;
;         PG8_STAGE(PG8_SB(1, 0), cB + kstep, voffB); PG8_STAGE(PG8_SA(1, 0), cA + kstep, voffA); PG8_STAGE(PG8_SB(1, 1), cB + hstep + kstep, voffB);
;         PG8_WAIT_V(6); PG8_BAR;
.LBB0_2037:
	s_add_u32 s14, s14, 0x4800000
	s_addc_u32 s15, s15, 0
	s_sext_i32_i8 s4, s18
	s_add_u32 s18, s13, 0x104000
	v_lshrrev_b32_e32 v20, 1, v18
	s_addc_u32 s53, s22, 0
	v_and_b32_e32 v20, 24, v20
	s_lshl_b32 s12, s12, 5
	v_and_b32_e32 v19, 15, v18
	v_lshlrev_b32_e32 v21, 1, v20
	v_lshlrev_b32_e32 v18, 2, v18
	s_and_b32 s22, s12, 0x60
	s_add_i32 m0, s43, 0x18000
	v_lshl_add_u64 v[10:11], v[10:11], 0, s[28:29]
	v_lshl_or_b32 v1, s23, 6, v19
	v_lshl_or_b32 v19, v19, 6, v21
	s_lshl_b32 s13, s23, 13
	v_and_b32_e32 v18, 32, v18
	s_lshl_b32 s12, s22, 7
	s_waitcnt vmcnt(2)
	s_barrier
	global_load_lds_dwordx4 v[10:11], off
	v_lshl_add_u64 v[8:9], v[8:9], 0, s[28:29]
	s_add_i32 m0, s43, 0x1a000
	s_add_i32 s54, s43, 0x8000
	s_add_i32 s55, s43, 0xa000
	v_bitop3_b32 v212, v19, s12, v18 bitop3:0xde
	v_add_u32_e32 v252, 0x10000, v212
	global_load_lds_dwordx4 v[8:9], off
	v_lshl_add_u64 v[6:7], v[6:7], 0, s[28:29]
	s_mov_b32 m0, s54
	s_add_u32 s12, s20, 0x80080
	v_bitop3_b32 v21, v19, s13, v18 bitop3:0xde
	global_load_lds_dwordx4 v[6:7], off
	v_lshl_add_u64 v[4:5], v[4:5], 0, s[28:29]
	s_mov_b32 m0, s55
	s_addc_u32 s13, s21, 0
	global_load_lds_dwordx4 v[4:5], off
	s_add_i32 m0, s43, 0x1c000
	s_nop 0
	global_load_lds_dwordx4 v2, s[12:13]
	v_lshl_add_u64 v[4:5], s[12:13], 0, v[184:185]
	s_add_i32 m0, s43, 0x1e000
	s_ashr_i32 s56, s5, 31
	global_load_lds_dwordx4 v[4:5], off
	v_lshlrev_b32_e32 v4, 15, v15
	v_and_b32_e32 v4, 0xffff0000, v4
	v_lshl_add_u32 v4, v16, 12, v4
	v_and_b32_e32 v5, 1, v15
	v_lshl_or_b32 v4, v5, 6, v4
	v_lshl_add_u32 v186, v17, 1, v4
	v_lshlrev_b32_e32 v4, 15, v12
	v_and_b32_e32 v4, 0xffff0000, v4
	s_waitcnt vmcnt(6)
	v_lshl_add_u32 v4, v13, 12, v4
	v_and_b32_e32 v5, 1, v12
	v_lshl_or_b32 v4, v5, 6, v4
	v_or_b32_e32 v213, s22, v20
	v_mov_b32_e32 v187, v3
	v_lshl_add_u32 v188, v14, 1, v4
	v_mov_b32_e32 v189, v3
	s_mov_b32 s57, 0
	v_add_u32_e32 v218, 0, v21
	s_barrier
	s_branch .LBB0_2039

; #define PG8_STAGE(bufoff, gbase, voff) do { _Pragma("unroll") for (int _i = 0; _i < 2; ++_i) \
;         __builtin_amdgcn_global_load_lds((const unsigned*)((const char*)(gbase) + (voff)[_i]), (PG8_LAS unsigned*)(lds + (bufoff) + ldsw + _i * 8192), 16, 0, 0); } while (0)
; #define PG8_LDA(dst, b, h) do { _Pragma("unroll") for (int m = 0; m < 4; ++m) _Pragma("unroll") for (int k = 0; k < 2; ++k) dst[m][k] = *(const PG8_LAS bf16x8*)(lds + PG8_SA(b, h) + aoff + m * 2048 + k * 1024); } while (0)
; #define PG8_LDB(dst, b, h) do { _Pragma("unroll") for (int n = 0; n < 2; ++n) _Pragma("unroll") for (int k = 0; k < 2; ++k) dst[n][k] = *(const PG8_LAS bf16x8*)(lds + PG8_SB(b, h) + boff + n * 2048 + k * 1024); } while (0)
; #define PG8_MMA(ai, bj, At, Bt) do { __builtin_amdgcn_s_setprio(1); _Pragma("unroll") for (int m = 0; m < 4; ++m) _Pragma("unroll") for (int n = 0; n < 2; ++n) _Pragma("unroll") for (int k = 0; k < 2; ++k) \
;         acc[ai][bj][m][n] = __builtin_amdgcn_mfma_f32_16x16x32_bf16(Bt[n][k], At[m][k], acc[ai][bj][m][n], 0, 0, 0); __builtin_amdgcn_s_setprio(0); } while (0)
; #define PG8_WAIT_V(n) asm volatile("s_waitcnt vmcnt(" #n ")" ::: "memory")
; #define PG8_BAR __builtin_amdgcn_s_barrier()
; template <class Epi, class Sched, bool ALIGN_EPI = false, bool SP2 = false>
; __device__ __forceinline__ void gemm_phase(PG8_LAS unsigned char* lds, const Gemm g, const Sched& S, const Epi& E) {
;     ...
;         for (int t = 0; t < nt; t += 2) {
;             const bool last = (t == nt - 2);
;             const char* a1 = cA + (size_t)(t + 1) * kstep;
;             const char* a2 = last ? nA : cA + (size_t)(t + 2) * kstep; const char* b2 = last ? nB : cB + (size_t)(t + 2) * kstep;
;             const char* a3 = a2 + kstep; const char* b3 = b2 + kstep;
;             if (last && has_next) S.a_ready(nxt);
;             if constexpr (SP2) {
;             PG8_LDB(B0, 0, 0); PG8_LDB(B1, 0, 1); PG8_SCHED; PG8_LDA(At, 0, 0); PG8_STAGE(PG8_SA(1, 1), a1 + hstep, voffA);
;             PG8_WAIT_V(8); PG8_WAIT_L(0); PG8_BAR; PG8_MMA(0, 0, At, B0); PG8_MMA(0, 1, At, B1); PG8_BAR; PG8_SCHED;
;             PG8_LDA(At, 0, 1); PG8_STAGE(PG8_SB(0, 0), b2, voffB); PG8_STAGE(PG8_SB(0, 1), b2 + hstep, voffB); PG8_STAGE(PG8_SA(0, 0), a2, voffA);
;             PG8_WAIT_V(8); PG8_WAIT_L(0); PG8_BAR; PG8_MMA(1, 0, At, B0); PG8_MMA(1, 1, At, B1); PG8_BAR; PG8_SCHED;
.LBB0_2046:
	s_add_u32 s20, s44, 0xfff80080
	s_addc_u32 s21, s45, -1
	s_add_i32 s30, 0, 0x10000
	s_cmp_eq_u32 s59, 28
	s_cselect_b32 s47, s12, s21
	s_cselect_b32 s46, s13, s20
	s_cselect_b32 s21, s23, s58
	s_cselect_b32 s20, s25, s33
	s_add_i32 s60, 0, 0x14000
	s_waitcnt vmcnt(0) lgkmcnt(0)
	ds_read_b128 v[60:63], v252
	ds_read_b128 v[64:67], v252 offset:1024
	ds_read_b128 v[76:79], v252 offset:2048
	ds_read_b128 v[80:83], v252 offset:3072
	ds_read_b128 v[148:151], v252 offset:16384
	ds_read_b128 v[152:155], v252 offset:17408
	ds_read_b128 v[156:159], v252 offset:18432
	ds_read_b128 v[160:163], v252 offset:19456
	s_add_i32 m0, s43, 0xc000
	ds_read_b128 v[164:167], v218
	ds_read_b128 v[168:171], v218 offset:1024
	ds_read_b128 v[172:175], v218 offset:2048
	ds_read_b128 v[176:179], v218 offset:3072
	ds_read_b128 v[190:193], v218 offset:4096
	ds_read_b128 v[194:197], v218 offset:5120
	ds_read_b128 v[198:201], v218 offset:6144
	ds_read_b128 v[202:205], v218 offset:7168
	global_load_lds_dwordx4 v188, s[44:45]
	s_add_i32 m0, s43, 0xe000
	s_nop 0
	global_load_lds_dwordx4 v186, s[44:45]
	s_waitcnt vmcnt(8)
	s_waitcnt lgkmcnt(0)
	s_barrier
	s_setprio 1
	s_waitcnt lgkmcnt(0)
	v_mfma_f32_16x16x32_bf16 v[144:147], v[60:63], v[164:167], v[144:147]
	v_mfma_f32_16x16x32_bf16 v[140:143], v[76:79], v[164:167], v[140:143]
	v_mfma_f32_16x16x32_bf16 v[136:139], v[60:63], v[172:175], v[136:139]
	v_mfma_f32_16x16x32_bf16 v[132:135], v[76:79], v[172:175], v[132:135]
	v_mfma_f32_16x16x32_bf16 v[112:115], v[60:63], v[190:193], v[112:115]
	v_mfma_f32_16x16x32_bf16 v[108:111], v[76:79], v[190:193], v[108:111]
	v_mfma_f32_16x16x32_bf16 v[104:107], v[60:63], v[198:201], v[104:107]
	v_mfma_f32_16x16x32_bf16 v[100:103], v[76:79], v[198:201], v[100:103]
	v_mfma_f32_16x16x32_bf16 v[144:147], v[64:67], v[168:171], v[144:147]
	v_mfma_f32_16x16x32_bf16 v[140:143], v[80:83], v[168:171], v[140:143]
	v_mfma_f32_16x16x32_bf16 v[136:139], v[64:67], v[176:179], v[136:139]
	v_mfma_f32_16x16x32_bf16 v[132:135], v[80:83], v[176:179], v[132:135]
	v_mfma_f32_16x16x32_bf16 v[112:115], v[64:67], v[194:197], v[112:115]
	v_mfma_f32_16x16x32_bf16 v[108:111], v[80:83], v[194:197], v[108:111]
	v_mfma_f32_16x16x32_bf16 v[104:107], v[64:67], v[202:205], v[104:107]
	v_mfma_f32_16x16x32_bf16 v[100:103], v[80:83], v[202:205], v[100:103]
	s_setprio 0
	s_setprio 1
	v_mfma_f32_16x16x32_bf16 v[128:131], v[148:151], v[164:167], v[128:131]
	v_mfma_f32_16x16x32_bf16 v[124:127], v[156:159], v[164:167], v[124:127]
	v_mfma_f32_16x16x32_bf16 v[120:123], v[148:151], v[172:175], v[120:123]
	v_mfma_f32_16x16x32_bf16 v[116:119], v[156:159], v[172:175], v[116:119]
	v_mfma_f32_16x16x32_bf16 v[96:99], v[148:151], v[190:193], v[96:99]
	v_mfma_f32_16x16x32_bf16 v[92:95], v[156:159], v[190:193], v[92:95]
	v_mfma_f32_16x16x32_bf16 v[88:91], v[148:151], v[198:201], v[88:91]
	v_mfma_f32_16x16x32_bf16 v[84:87], v[156:159], v[198:201], v[84:87]
	v_mfma_f32_16x16x32_bf16 v[128:131], v[152:155], v[168:171], v[128:131]
	v_mfma_f32_16x16x32_bf16 v[124:127], v[160:163], v[168:171], v[124:127]
	v_mfma_f32_16x16x32_bf16 v[120:123], v[152:155], v[176:179], v[120:123]
	v_mfma_f32_16x16x32_bf16 v[116:119], v[160:163], v[176:179], v[116:119]
	v_mfma_f32_16x16x32_bf16 v[96:99], v[152:155], v[194:197], v[96:99]
	v_mfma_f32_16x16x32_bf16 v[92:95], v[160:163], v[194:197], v[92:95]
	v_mfma_f32_16x16x32_bf16 v[88:91], v[152:155], v[202:205], v[88:91]
	v_mfma_f32_16x16x32_bf16 v[84:87], v[160:163], v[202:205], v[84:87]
	s_setprio 0
	s_barrier
	s_add_i32 s30, s30, s9
	s_mov_b32 m0, s30
	ds_read_b128 v[164:167], v218 offset:16384
	ds_read_b128 v[168:171], v218 offset:17408
	ds_read_b128 v[172:175], v218 offset:18432
	ds_read_b128 v[176:179], v218 offset:19456
	ds_read_b128 v[190:193], v218 offset:20480
	ds_read_b128 v[194:197], v218 offset:21504
	ds_read_b128 v[198:201], v218 offset:22528
	ds_read_b128 v[202:205], v218 offset:23552
	global_load_lds_dwordx4 v2, s[20:21]
	s_add_i32 m0, s30, 0x2000
	s_add_u32 s30, s20, 0x80000
	s_addc_u32 s31, s21, 0
	s_add_u32 s98, s20, s28
	s_addc_u32 s99, s21, s29
	s_add_u32 s94, s46, s28
	s_addc_u32 s95, s47, s29
	s_add_i32 s60, s60, s9
	global_load_lds_dwordx4 v184, s[20:21]
	s_mov_b32 m0, s60
	s_nop 0
	global_load_lds_dwordx4 v2, s[30:31]
	s_add_i32 m0, s60, 0x2000
	s_nop 0
	global_load_lds_dwordx4 v184, s[30:31]
	s_mov_b32 m0, s43
	s_nop 0
	global_load_lds_dwordx4 v180, s[46:47]
	s_mov_b32 m0, s50
	s_nop 0
	global_load_lds_dwordx4 v182, s[46:47]
	s_waitcnt vmcnt(8)
	s_waitcnt lgkmcnt(0)
	s_barrier
	s_setprio 1
	s_waitcnt lgkmcnt(0)
	v_mfma_f32_16x16x32_bf16 v[72:75], v[60:63], v[164:167], v[72:75]
	v_mfma_f32_16x16x32_bf16 v[68:71], v[76:79], v[164:167], v[68:71]
	v_mfma_f32_16x16x32_bf16 v[56:59], v[60:63], v[172:175], v[56:59]
	v_mfma_f32_16x16x32_bf16 v[52:55], v[76:79], v[172:175], v[52:55]
	v_mfma_f32_16x16x32_bf16 v[32:35], v[60:63], v[190:193], v[32:35]
	v_mfma_f32_16x16x32_bf16 v[28:31], v[76:79], v[190:193], v[28:31]
	v_mfma_f32_16x16x32_bf16 v[24:27], v[60:63], v[198:201], v[24:27]
	v_mfma_f32_16x16x32_bf16 v[20:23], v[76:79], v[198:201], v[20:23]
	v_mfma_f32_16x16x32_bf16 v[72:75], v[64:67], v[168:171], v[72:75]
	v_mfma_f32_16x16x32_bf16 v[68:71], v[80:83], v[168:171], v[68:71]
	v_mfma_f32_16x16x32_bf16 v[56:59], v[64:67], v[176:179], v[56:59]
	v_mfma_f32_16x16x32_bf16 v[52:55], v[80:83], v[176:179], v[52:55]
	v_mfma_f32_16x16x32_bf16 v[32:35], v[64:67], v[194:197], v[32:35]
	v_mfma_f32_16x16x32_bf16 v[28:31], v[80:83], v[194:197], v[28:31]
	v_mfma_f32_16x16x32_bf16 v[24:27], v[64:67], v[202:205], v[24:27]
	v_mfma_f32_16x16x32_bf16 v[20:23], v[80:83], v[202:205], v[20:23]
	s_setprio 0
	s_setprio 1
	v_mfma_f32_16x16x32_bf16 v[48:51], v[148:151], v[164:167], v[48:51]
	v_mfma_f32_16x16x32_bf16 v[44:47], v[156:159], v[164:167], v[44:47]
	v_mfma_f32_16x16x32_bf16 v[40:43], v[148:151], v[172:175], v[40:43]
	v_mfma_f32_16x16x32_bf16 v[36:39], v[156:159], v[172:175], v[36:39]
	v_mfma_f32_16x16x32_bf16 v[16:19], v[148:151], v[190:193], v[16:19]
	v_mfma_f32_16x16x32_bf16 v[12:15], v[156:159], v[190:193], v[12:15]
	v_mfma_f32_16x16x32_bf16 v[8:11], v[148:151], v[198:201], v[8:11]
	v_mfma_f32_16x16x32_bf16 v[4:7], v[156:159], v[198:201], v[4:7]
	v_mfma_f32_16x16x32_bf16 v[48:51], v[152:155], v[168:171], v[48:51]
	v_mfma_f32_16x16x32_bf16 v[44:47], v[160:163], v[168:171], v[44:47]
	v_mfma_f32_16x16x32_bf16 v[40:43], v[152:155], v[176:179], v[40:43]
	v_mfma_f32_16x16x32_bf16 v[36:39], v[160:163], v[176:179], v[36:39]
	v_mfma_f32_16x16x32_bf16 v[16:19], v[152:155], v[194:197], v[16:19]
	v_mfma_f32_16x16x32_bf16 v[12:15], v[160:163], v[194:197], v[12:15]
	v_mfma_f32_16x16x32_bf16 v[8:11], v[152:155], v[202:205], v[8:11]
	v_mfma_f32_16x16x32_bf16 v[4:7], v[160:163], v[202:205], v[4:7]
	s_setprio 0
	s_barrier
; #define PG8_STAGE(bufoff, gbase, voff) do { _Pragma("unroll") for (int _i = 0; _i < 2; ++_i) \
;         __builtin_amdgcn_global_load_lds((const unsigned*)((const char*)(gbase) + (voff)[_i]), (PG8_LAS unsigned*)(lds + (bufoff) + ldsw + _i * 8192), 16, 0, 0); } while (0)
; #define PG8_LDA(dst, b, h) do { _Pragma("unroll") for (int m = 0; m < 4; ++m) _Pragma("unroll") for (int k = 0; k < 2; ++k) dst[m][k] = *(const PG8_LAS bf16x8*)(lds + PG8_SA(b, h) + aoff + m * 2048 + k * 1024); } while (0)
; #define PG8_LDB(dst, b, h) do { _Pragma("unroll") for (int n = 0; n < 2; ++n) _Pragma("unroll") for (int k = 0; k < 2; ++k) dst[n][k] = *(const PG8_LAS bf16x8*)(lds + PG8_SB(b, h) + boff + n * 2048 + k * 1024); } while (0)
; #define PG8_MMA(ai, bj, At, Bt) do { __builtin_amdgcn_s_setprio(1); _Pragma("unroll") for (int m = 0; m < 4; ++m) _Pragma("unroll") for (int n = 0; n < 2; ++n) _Pragma("unroll") for (int k = 0; k < 2; ++k) \
;         acc[ai][bj][m][n] = __builtin_amdgcn_mfma_f32_16x16x32_bf16(Bt[n][k], At[m][k], acc[ai][bj][m][n], 0, 0, 0); __builtin_amdgcn_s_setprio(0); } while (0)
; #define PG8_WAIT_V(n) asm volatile("s_waitcnt vmcnt(" #n ")" ::: "memory")
; #define PG8_WAIT_L(n) asm volatile("s_waitcnt lgkmcnt(" #n ")" ::: "memory")
; #define PG8_BAR __builtin_amdgcn_s_barrier()
; #define PG8_SCHED __builtin_amdgcn_sched_barrier(0)
; template <class Epi, class Sched, bool ALIGN_EPI = false, bool SP2 = false>
; __device__ __forceinline__ void gemm_phase(PG8_LAS unsigned char* lds, const Gemm g, const Sched& S, const Epi& E) {
;     ...
;             PG8_WAIT_V(8); PG8_WAIT_L(0); PG8_BAR; PG8_MMA(1, 0, At, B0); PG8_MMA(1, 1, At, B1); PG8_BAR; PG8_SCHED;
;             PG8_LDB(B0, 1, 0); PG8_LDB(B1, 1, 1); PG8_SCHED; PG8_LDA(At, 1, 0); PG8_STAGE(PG8_SA(0, 1), a2 + hstep, voffA);
;             PG8_WAIT_V(8); PG8_WAIT_L(0); PG8_BAR; PG8_MMA(0, 0, At, B0); PG8_MMA(0, 1, At, B1); PG8_BAR; PG8_SCHED;
;             PG8_LDA(At, 1, 1); PG8_STAGE(PG8_SB(1, 0), b3, voffB); PG8_STAGE(PG8_SB(1, 1), b3 + hstep, voffB); PG8_STAGE(PG8_SA(1, 0), a3, voffA);
;             PG8_WAIT_V(8); PG8_WAIT_L(0); PG8_BAR; PG8_MMA(1, 0, At, B0); PG8_MMA(1, 1, At, B1); PG8_BAR; PG8_SCHED;
	s_add_i32 s60, 0, 0x18000
	s_add_i32 s61, 0, 0x1c000
	ds_read_b128 v[60:63], v252 offset:32768
	ds_read_b128 v[64:67], v252 offset:33792
	ds_read_b128 v[76:79], v252 offset:34816
	ds_read_b128 v[80:83], v252 offset:35840
	ds_read_b128 v[148:151], v252 offset:49152
	ds_read_b128 v[152:155], v252 offset:50176
	ds_read_b128 v[156:159], v252 offset:51200
	ds_read_b128 v[160:163], v252 offset:52224
	s_add_u32 s30, s46, 0x80000
	s_addc_u32 s31, s47, 0
	s_mov_b32 m0, s51
	ds_read_b128 v[164:167], v218 offset:32768
	ds_read_b128 v[168:171], v218 offset:33792
	ds_read_b128 v[172:175], v218 offset:34816
	ds_read_b128 v[176:179], v218 offset:35840
	ds_read_b128 v[190:193], v218 offset:36864
	ds_read_b128 v[194:197], v218 offset:37888
	ds_read_b128 v[198:201], v218 offset:38912
	ds_read_b128 v[202:205], v218 offset:39936
	global_load_lds_dwordx4 v180, s[30:31]
	s_mov_b32 m0, s52
	s_nop 0
	global_load_lds_dwordx4 v182, s[30:31]
	s_waitcnt vmcnt(8)
	s_waitcnt lgkmcnt(0)
	s_barrier
	s_setprio 1
	s_waitcnt lgkmcnt(0)
	v_mfma_f32_16x16x32_bf16 v[144:147], v[60:63], v[164:167], v[144:147]
	v_mfma_f32_16x16x32_bf16 v[140:143], v[76:79], v[164:167], v[140:143]
	v_mfma_f32_16x16x32_bf16 v[136:139], v[60:63], v[172:175], v[136:139]
	v_mfma_f32_16x16x32_bf16 v[132:135], v[76:79], v[172:175], v[132:135]
	v_mfma_f32_16x16x32_bf16 v[112:115], v[60:63], v[190:193], v[112:115]
	v_mfma_f32_16x16x32_bf16 v[108:111], v[76:79], v[190:193], v[108:111]
	v_mfma_f32_16x16x32_bf16 v[104:107], v[60:63], v[198:201], v[104:107]
	v_mfma_f32_16x16x32_bf16 v[100:103], v[76:79], v[198:201], v[100:103]
	v_mfma_f32_16x16x32_bf16 v[144:147], v[64:67], v[168:171], v[144:147]
	v_mfma_f32_16x16x32_bf16 v[140:143], v[80:83], v[168:171], v[140:143]
	v_mfma_f32_16x16x32_bf16 v[136:139], v[64:67], v[176:179], v[136:139]
	v_mfma_f32_16x16x32_bf16 v[132:135], v[80:83], v[176:179], v[132:135]
	v_mfma_f32_16x16x32_bf16 v[112:115], v[64:67], v[194:197], v[112:115]
	v_mfma_f32_16x16x32_bf16 v[108:111], v[80:83], v[194:197], v[108:111]
	v_mfma_f32_16x16x32_bf16 v[104:107], v[64:67], v[202:205], v[104:107]
	v_mfma_f32_16x16x32_bf16 v[100:103], v[80:83], v[202:205], v[100:103]
	s_setprio 0
	s_setprio 1
	v_mfma_f32_16x16x32_bf16 v[128:131], v[148:151], v[164:167], v[128:131]
	v_mfma_f32_16x16x32_bf16 v[124:127], v[156:159], v[164:167], v[124:127]
	v_mfma_f32_16x16x32_bf16 v[120:123], v[148:151], v[172:175], v[120:123]
	v_mfma_f32_16x16x32_bf16 v[116:119], v[156:159], v[172:175], v[116:119]
	v_mfma_f32_16x16x32_bf16 v[96:99], v[148:151], v[190:193], v[96:99]
	v_mfma_f32_16x16x32_bf16 v[92:95], v[156:159], v[190:193], v[92:95]
	v_mfma_f32_16x16x32_bf16 v[88:91], v[148:151], v[198:201], v[88:91]
	v_mfma_f32_16x16x32_bf16 v[84:87], v[156:159], v[198:201], v[84:87]
	v_mfma_f32_16x16x32_bf16 v[128:131], v[152:155], v[168:171], v[128:131]
	v_mfma_f32_16x16x32_bf16 v[124:127], v[160:163], v[168:171], v[124:127]
	v_mfma_f32_16x16x32_bf16 v[120:123], v[152:155], v[176:179], v[120:123]
	v_mfma_f32_16x16x32_bf16 v[116:119], v[160:163], v[176:179], v[116:119]
	v_mfma_f32_16x16x32_bf16 v[96:99], v[152:155], v[194:197], v[96:99]
	v_mfma_f32_16x16x32_bf16 v[92:95], v[160:163], v[194:197], v[92:95]
	v_mfma_f32_16x16x32_bf16 v[88:91], v[152:155], v[202:205], v[88:91]
	v_mfma_f32_16x16x32_bf16 v[84:87], v[160:163], v[202:205], v[84:87]
	s_setprio 0
	s_barrier
	s_add_i32 s30, s60, s9
	s_mov_b32 m0, s30
	ds_read_b128 v[164:167], v218 offset:49152
	ds_read_b128 v[168:171], v218 offset:50176
	ds_read_b128 v[172:175], v218 offset:51200
	ds_read_b128 v[176:179], v218 offset:52224
	ds_read_b128 v[190:193], v218 offset:53248
	ds_read_b128 v[194:197], v218 offset:54272
	ds_read_b128 v[198:201], v218 offset:55296
	ds_read_b128 v[202:205], v218 offset:56320
	global_load_lds_dwordx4 v2, s[98:99]
	s_add_i32 m0, s30, 0x2000
	s_add_u32 s20, s20, 0x80080
	s_addc_u32 s21, s21, 0
	s_add_i32 s30, s61, s9
	global_load_lds_dwordx4 v184, s[98:99]
	s_mov_b32 m0, s30
	s_nop 0
	global_load_lds_dwordx4 v2, s[20:21]
	s_add_i32 m0, s30, 0x2000
	s_nop 0
	global_load_lds_dwordx4 v184, s[20:21]
	s_mov_b32 m0, s54
	s_nop 0
	global_load_lds_dwordx4 v180, s[94:95]
	s_mov_b32 m0, s55
	s_nop 0
	global_load_lds_dwordx4 v182, s[94:95]
	s_waitcnt vmcnt(8)
	s_waitcnt lgkmcnt(0)
	s_barrier
	s_setprio 1
	s_waitcnt lgkmcnt(0)
	v_mfma_f32_16x16x32_bf16 v[72:75], v[60:63], v[164:167], v[72:75]
	v_mfma_f32_16x16x32_bf16 v[68:71], v[76:79], v[164:167], v[68:71]
	v_mfma_f32_16x16x32_bf16 v[56:59], v[60:63], v[172:175], v[56:59]
	v_mfma_f32_16x16x32_bf16 v[52:55], v[76:79], v[172:175], v[52:55]
	v_mfma_f32_16x16x32_bf16 v[32:35], v[60:63], v[190:193], v[32:35]
	v_mfma_f32_16x16x32_bf16 v[28:31], v[76:79], v[190:193], v[28:31]
	v_mfma_f32_16x16x32_bf16 v[24:27], v[60:63], v[198:201], v[24:27]
	v_mfma_f32_16x16x32_bf16 v[20:23], v[76:79], v[198:201], v[20:23]
	v_mfma_f32_16x16x32_bf16 v[72:75], v[64:67], v[168:171], v[72:75]
	v_mfma_f32_16x16x32_bf16 v[68:71], v[80:83], v[168:171], v[68:71]
	v_mfma_f32_16x16x32_bf16 v[56:59], v[64:67], v[176:179], v[56:59]
	v_mfma_f32_16x16x32_bf16 v[52:55], v[80:83], v[176:179], v[52:55]
	v_mfma_f32_16x16x32_bf16 v[32:35], v[64:67], v[194:197], v[32:35]
	v_mfma_f32_16x16x32_bf16 v[28:31], v[80:83], v[194:197], v[28:31]
	v_mfma_f32_16x16x32_bf16 v[24:27], v[64:67], v[202:205], v[24:27]
	v_mfma_f32_16x16x32_bf16 v[20:23], v[80:83], v[202:205], v[20:23]
	s_setprio 0
	s_setprio 1
	v_mfma_f32_16x16x32_bf16 v[48:51], v[148:151], v[164:167], v[48:51]
	v_mfma_f32_16x16x32_bf16 v[44:47], v[156:159], v[164:167], v[44:47]
	v_mfma_f32_16x16x32_bf16 v[40:43], v[148:151], v[172:175], v[40:43]
	v_mfma_f32_16x16x32_bf16 v[36:39], v[156:159], v[172:175], v[36:39]
	v_mfma_f32_16x16x32_bf16 v[16:19], v[148:151], v[190:193], v[16:19]
	v_mfma_f32_16x16x32_bf16 v[12:15], v[156:159], v[190:193], v[12:15]
	v_mfma_f32_16x16x32_bf16 v[8:11], v[148:151], v[198:201], v[8:11]
	v_mfma_f32_16x16x32_bf16 v[4:7], v[156:159], v[198:201], v[4:7]
	v_mfma_f32_16x16x32_bf16 v[48:51], v[152:155], v[168:171], v[48:51]
	v_mfma_f32_16x16x32_bf16 v[44:47], v[160:163], v[168:171], v[44:47]
	v_mfma_f32_16x16x32_bf16 v[40:43], v[152:155], v[176:179], v[40:43]
	v_mfma_f32_16x16x32_bf16 v[36:39], v[160:163], v[176:179], v[36:39]
	v_mfma_f32_16x16x32_bf16 v[16:19], v[152:155], v[194:197], v[16:19]
	v_mfma_f32_16x16x32_bf16 v[12:15], v[160:163], v[194:197], v[12:15]
	v_mfma_f32_16x16x32_bf16 v[8:11], v[152:155], v[202:205], v[8:11]
	v_mfma_f32_16x16x32_bf16 v[4:7], v[160:163], v[202:205], v[4:7]
	s_setprio 0
	s_barrier
;     __device__ __forceinline__ void operator()(const f32x4 (&acc)[2][2][4][2], const Unit& u, int wr, int wc, int fr, int fq) const {
;         const int row0 = u.pm * BM + wr * 64 + fr; const int col0 = u.pn * BM + wc * 32 + 8 * fq;
;         const float* gp = gate + (size_t)((u.pm * BM) >> 12) * gstride + col0;
;         f32x4 gv[2][2];
; #pragma unroll
;         for (int bj = 0; bj < 2; ++bj)
; #pragma unroll
;             for (int n = 0; n < 2; ++n) gv[bj][n] = *(const f32x4*)(gp + bj * HALF + n * 4);
;         if (base_f32) { const float* bp = (const float*)base;
; #pragma unroll
;             for (int ai = 0; ai < 2; ++ai)
; #pragma unroll
;                 for (int m2 = 0; m2 < 2; ++m2) { f32x4 bs[2][2][2];
; #pragma unroll
;                     for (int mm = 0; mm < 2; ++mm) { const size_t off = (size_t)(row0 + ai * HALF + (2 * m2 + mm) * 16) * ldc + col0;
; #pragma unroll
;                         for (int bj = 0; bj < 2; ++bj)
; #pragma unroll
;                             for (int n = 0; n < 2; ++n) bs[mm][bj][n] = *(const f32x4*)(bp + off + bj * HALF + n * 4); }
; #pragma unroll
;                     for (int mm = 0; mm < 2; ++mm) { const size_t off = (size_t)(row0 + ai * HALF + (2 * m2 + mm) * 16) * ldc + col0;
; #pragma unroll
;                         for (int bj = 0; bj < 2; ++bj) { const f32x4 v0 = bs[mm][bj][0] + gv[bj][0] * acc[ai][bj][2 * m2 + mm][0], v1 = bs[mm][bj][1] + gv[bj][1] * acc[ai][bj][2 * m2 + mm][1];
;                             u32x4 w; w.x = cvt_pk_bf16(v0[0], v0[1]); w.y = cvt_pk_bf16(v0[2], v0[3]); w.z = cvt_pk_bf16(v1[0], v1[1]); w.w = cvt_pk_bf16(v1[2], v1[3]);
;                             *(u32x4*)(out + off + bj * HALF) = w; } }
;                     asm volatile("" ::: "memory"); }
;         } else { const bf16_t* bp = (const bf16_t*)base;
; #pragma unroll
;             for (int ai = 0; ai < 2; ++ai) { u32x4 bs[4][2];
; #pragma unroll
;                 for (int m = 0; m < 4; ++m) { const size_t off = (size_t)(row0 + ai * HALF + m * 16) * ldc + col0;
; #pragma unroll
;                     for (int bj = 0; bj < 2; ++bj) bs[m][bj] = *(const u32x4*)(bp + off + bj * HALF); }
; #pragma unroll
;                 for (int m = 0; m < 4; ++m) { const size_t off = (size_t)(row0 + ai * HALF + m * 16) * ldc + col0;
; #pragma unroll
	s_add_i32 s59, s59, 2
	s_add_u32 s33, s33, 0x100
	s_addc_u32 s58, s58, 0
	s_add_u32 s44, s44, 0x100
	s_addc_u32 s45, s45, 0
	s_cmp_gt_u32 s59, 29
	s_cbranch_scc0 .LBB0_2046
	v_lshl_or_b32 v202, s4, 8, v213
	s_ashr_i32 s4, s42, 4
	s_mul_hi_i32 s13, s4, 0xc000
	s_mul_i32 s4, s4, 0xc000
	s_add_u32 s12, s18, s4
	s_addc_u32 s13, s53, s13
	v_ashrrev_i32_e32 v203, 31, v202
	v_lshl_add_u64 v[60:61], v[202:203], 2, s[12:13]
	flat_load_dwordx4 v[80:83], v[60:61]
	flat_load_dwordx4 v[76:79], v[60:61] offset:16
	flat_load_dwordx4 v[64:67], v[60:61] offset:512
	s_nop 0
	flat_load_dwordx4 v[60:63], v[60:61] offset:528
	v_lshl_add_u32 v192, s42, 8, v1
	v_ashrrev_i32_e32 v193, 31, v192
	v_or_b32_e32 v198, 16, v192
	v_or_b32_e32 v196, 32, v192
	v_or_b32_e32 v194, 48, v192
	v_lshlrev_b64 v[200:201], 11, v[192:193]
	s_and_b64 vcc, exec, s[16:17]
	v_lshlrev_b64 v[190:191], 1, v[202:203]
	v_ashrrev_i32_e32 v199, 31, v198
	v_ashrrev_i32_e32 v197, 31, v196
	v_ashrrev_i32_e32 v195, 31, v194
	s_cbranch_vccz .LBB0_2049
	v_lshl_add_u64 v[204:205], s[26:27], 0, v[190:191]
	v_lshlrev_b64 v[156:157], 1, v[200:201]
	v_lshl_add_u64 v[148:149], v[204:205], 0, v[156:157]
	v_lshlrev_b64 v[152:153], 12, v[198:199]
	flat_load_dwordx4 v[172:175], v[148:149]
	flat_load_dwordx4 v[168:171], v[148:149] offset:256
	v_lshl_add_u64 v[148:149], v[204:205], 0, v[152:153]
	flat_load_dwordx4 v[164:167], v[148:149]
	s_nop 0
	flat_load_dwordx4 v[148:151], v[148:149] offset:256
	v_lshlrev_b64 v[208:209], 12, v[196:197]
	v_lshlrev_b64 v[206:207], 12, v[194:195]
	v_lshl_add_u64 v[154:155], v[204:205], 0, v[208:209]
	v_lshl_add_u64 v[210:211], v[204:205], 0, v[206:207]
	v_lshl_add_u64 v[214:215], s[14:15], 0, v[156:157]
	v_lshl_add_u64 v[216:217], s[14:15], 0, v[152:153]
	flat_load_dwordx4 v[176:179], v[154:155]
	flat_load_dwordx4 v[160:163], v[154:155] offset:256
	flat_load_dwordx4 v[156:159], v[210:211]
	s_nop 0
	flat_load_dwordx4 v[152:155], v[210:211] offset:256
	v_lshl_add_u64 v[210:211], v[216:217], 0, v[190:191]
	v_lshl_add_u64 v[214:215], v[214:215], 0, v[190:191]
	s_mov_b64 s[12:13], 0x80000
	s_waitcnt vmcnt(0) lgkmcnt(0)
	v_lshlrev_b32_e32 v216, 16, v172
	v_and_b32_e32 v172, 0xffff0000, v172
	v_lshlrev_b32_e32 v217, 16, v173
	v_and_b32_e32 v173, 0xffff0000, v173
	v_lshlrev_b32_e32 v219, 16, v174
	v_and_b32_e32 v174, 0xffff0000, v174
	v_lshlrev_b32_e32 v220, 16, v175
	v_and_b32_e32 v175, 0xffff0000, v175
	v_lshlrev_b32_e32 v221, 16, v168
	v_and_b32_e32 v168, 0xffff0000, v168
	v_lshlrev_b32_e32 v225, 16, v164
	v_and_b32_e32 v226, 0xffff0000, v164
	v_fmac_f32_e32 v216, v144, v80
	v_fmac_f32_e32 v172, v145, v81
	v_cvt_pk_bf16_f32 v164, v216, v172
	v_lshlrev_b32_e32 v222, 16, v169
	v_and_b32_e32 v169, 0xffff0000, v169
	v_lshlrev_b32_e32 v223, 16, v170
	v_and_b32_e32 v170, 0xffff0000, v170
	v_lshlrev_b32_e32 v224, 16, v171
	v_and_b32_e32 v171, 0xffff0000, v171
	v_lshlrev_b32_e32 v227, 16, v165
	v_and_b32_e32 v229, 0xffff0000, v165
	v_lshlrev_b32_e32 v232, 16, v166
	v_and_b32_e32 v233, 0xffff0000, v166
	v_lshlrev_b32_e32 v240, 16, v167
	v_and_b32_e32 v241, 0xffff0000, v167
	v_fmac_f32_e32 v217, v146, v82
	v_fmac_f32_e32 v173, v147, v83
	v_fmac_f32_e32 v219, v140, v76
	v_fmac_f32_e32 v174, v141, v77
	v_fmac_f32_e32 v220, v142, v78
	v_fmac_f32_e32 v175, v143, v79
	v_fmac_f32_e32 v221, v128, v64
	v_fmac_f32_e32 v168, v129, v65
	v_cvt_pk_bf16_f32 v165, v217, v173
	v_cvt_pk_bf16_f32 v166, v219, v174
	v_cvt_pk_bf16_f32 v167, v220, v175
	flat_store_dwordx4 v[214:215], v[164:167]
	v_fmac_f32_e32 v222, v130, v66
	v_fmac_f32_e32 v169, v131, v67
	v_cvt_pk_bf16_f32 v164, v221, v168
	v_fmac_f32_e32 v223, v124, v60
	v_fmac_f32_e32 v170, v125, v61
	v_fmac_f32_e32 v224, v126, v62
	v_fmac_f32_e32 v171, v127, v63
	v_fmac_f32_e32 v225, v136, v80
	v_fmac_f32_e32 v226, v137, v81
	v_cvt_pk_bf16_f32 v165, v222, v169
	v_cvt_pk_bf16_f32 v166, v223, v170
	v_cvt_pk_bf16_f32 v167, v224, v171
	flat_store_dwordx4 v[214:215], v[164:167] offset:256
	v_lshlrev_b32_e32 v242, 16, v148
	v_and_b32_e32 v148, 0xffff0000, v148
	v_cvt_pk_bf16_f32 v164, v225, v226
	v_fmac_f32_e32 v227, v138, v82
	v_fmac_f32_e32 v229, v139, v83
	v_fmac_f32_e32 v232, v132, v76
	v_fmac_f32_e32 v233, v133, v77
	v_fmac_f32_e32 v240, v134, v78
	v_fmac_f32_e32 v241, v135, v79
	v_cvt_pk_bf16_f32 v165, v227, v229
	v_cvt_pk_bf16_f32 v166, v232, v233
	v_cvt_pk_bf16_f32 v167, v240, v241
	flat_store_dwordx4 v[210:211], v[164:167]
	v_fmac_f32_e32 v148, v121, v65
	v_fmac_f32_e32 v242, v120, v64
	v_lshlrev_b32_e32 v164, 16, v149
	v_and_b32_e32 v149, 0xffff0000, v149
	v_fmac_f32_e32 v164, v122, v66
	v_fmac_f32_e32 v149, v123, v67
	v_cvt_pk_bf16_f32 v148, v242, v148
	v_cvt_pk_bf16_f32 v149, v164, v149
	v_lshlrev_b32_e32 v164, 16, v150
	v_and_b32_e32 v150, 0xffff0000, v150
	v_fmac_f32_e32 v164, v116, v60
	v_fmac_f32_e32 v150, v117, v61
	v_cvt_pk_bf16_f32 v150, v164, v150
	v_lshlrev_b32_e32 v164, 16, v151
	v_and_b32_e32 v151, 0xffff0000, v151
	v_fmac_f32_e32 v151, v119, v63
	v_fmac_f32_e32 v164, v118, v62
	v_cvt_pk_bf16_f32 v151, v164, v151
	flat_store_dwordx4 v[210:211], v[148:151] offset:256
	v_and_b32_e32 v164, 0xffff0000, v179
	v_fmac_f32_e32 v164, v111, v79
	v_lshlrev_b32_e32 v148, 16, v176
	v_and_b32_e32 v149, 0xffff0000, v176
	v_fmac_f32_e32 v148, v112, v80
	v_fmac_f32_e32 v149, v113, v81
	v_cvt_pk_bf16_f32 v148, v148, v149
	v_lshlrev_b32_e32 v149, 16, v177
	v_and_b32_e32 v150, 0xffff0000, v177
	v_fmac_f32_e32 v149, v114, v82
	v_fmac_f32_e32 v150, v115, v83
	v_cvt_pk_bf16_f32 v149, v149, v150
	v_lshlrev_b32_e32 v150, 16, v178
	v_and_b32_e32 v151, 0xffff0000, v178
	v_fmac_f32_e32 v150, v108, v76
	v_fmac_f32_e32 v151, v109, v77
	v_cvt_pk_bf16_f32 v150, v150, v151
; __device__ __forceinline__ unsigned cvt_pk_bf16(float lo, float hi) { unsigned r; asm volatile("v_cvt_pk_bf16_f32 %0, %1, %2" : "=v"(r) : "v"(lo), "v"(hi)); return r; }
;     __device__ __forceinline__ void operator()(const f32x4 (&acc)[2][2][4][2], const Unit& u, int wr, int wc, int fr, int fq) const {
;     ...
;                 for (int m = 0; m < 4; ++m) { const size_t off = (size_t)(row0 + ai * HALF + m * 16) * ldc + col0;
; #pragma unroll
;                     for (int bj = 0; bj < 2; ++bj) bs[m][bj] = *(const u32x4*)(bp + off + bj * HALF); }
;     ...
;                 for (int m = 0; m < 4; ++m) { const size_t off = (size_t)(row0 + ai * HALF + m * 16) * ldc + col0;
; #pragma unroll
;                     for (int bj = 0; bj < 2; ++bj) { const u32x4 r = bs[m][bj]; const f32x4 a0 = acc[ai][bj][m][0], a1 = acc[ai][bj][m][1];
;                         u32x4 w;
;                         w.x = cvt_pk_bf16(__builtin_bit_cast(float, r.x << 16) + gv[bj][0][0] * a0[0], __builtin_bit_cast(float, r.x & 0xffff0000u) + gv[bj][0][1] * a0[1]);
;                         w.y = cvt_pk_bf16(__builtin_bit_cast(float, r.y << 16) + gv[bj][0][2] * a0[2], __builtin_bit_cast(float, r.y & 0xffff0000u) + gv[bj][0][3] * a0[3]);
;                         w.z = cvt_pk_bf16(__builtin_bit_cast(float, r.z << 16) + gv[bj][1][0] * a1[0], __builtin_bit_cast(float, r.z & 0xffff0000u) + gv[bj][1][1] * a1[1]);
;                         w.w = cvt_pk_bf16(__builtin_bit_cast(float, r.w << 16) + gv[bj][1][2] * a1[2], __builtin_bit_cast(float, r.w & 0xffff0000u) + gv[bj][1][3] * a1[3]);
;                         *(u32x4*)(out + off + bj * HALF) = w; } }
	v_lshlrev_b32_e32 v151, 16, v179
	v_fmac_f32_e32 v151, v110, v78
	v_cvt_pk_bf16_f32 v151, v151, v164
	v_lshl_add_u64 v[164:165], s[14:15], 0, v[208:209]
	v_lshl_add_u64 v[164:165], v[164:165], 0, v[190:191]
	flat_store_dwordx4 v[164:165], v[148:151]
	s_nop 1
	v_lshlrev_b32_e32 v148, 16, v160
	v_and_b32_e32 v149, 0xffff0000, v160
	v_fmac_f32_e32 v148, v96, v64
	v_fmac_f32_e32 v149, v97, v65
	v_cvt_pk_bf16_f32 v148, v148, v149
	v_lshlrev_b32_e32 v149, 16, v161
	v_and_b32_e32 v150, 0xffff0000, v161
	v_fmac_f32_e32 v149, v98, v66
	v_fmac_f32_e32 v150, v99, v67
	v_cvt_pk_bf16_f32 v149, v149, v150
	v_lshlrev_b32_e32 v150, 16, v162
	v_and_b32_e32 v151, 0xffff0000, v162
	v_fmac_f32_e32 v150, v92, v60
	v_fmac_f32_e32 v151, v93, v61
	v_cvt_pk_bf16_f32 v150, v150, v151
	v_lshlrev_b32_e32 v151, 16, v163
	v_fmac_f32_e32 v151, v94, v62
	v_and_b32_e32 v160, 0xffff0000, v163
	v_fmac_f32_e32 v160, v95, v63
	v_cvt_pk_bf16_f32 v151, v151, v160
	flat_store_dwordx4 v[164:165], v[148:151] offset:256
	s_nop 1
	v_lshlrev_b32_e32 v148, 16, v156
	v_and_b32_e32 v149, 0xffff0000, v156
	v_fmac_f32_e32 v148, v104, v80
	v_fmac_f32_e32 v149, v105, v81
	v_cvt_pk_bf16_f32 v148, v148, v149
	v_lshlrev_b32_e32 v149, 16, v157
	v_and_b32_e32 v150, 0xffff0000, v157
	v_fmac_f32_e32 v149, v106, v82
	v_fmac_f32_e32 v150, v107, v83
	v_cvt_pk_bf16_f32 v149, v149, v150
	v_lshlrev_b32_e32 v150, 16, v158
	v_and_b32_e32 v151, 0xffff0000, v158
	v_fmac_f32_e32 v150, v100, v76
	v_fmac_f32_e32 v151, v101, v77
	v_cvt_pk_bf16_f32 v150, v150, v151
	v_lshlrev_b32_e32 v151, 16, v159
	v_and_b32_e32 v156, 0xffff0000, v159
	v_fmac_f32_e32 v151, v102, v78
	v_fmac_f32_e32 v156, v103, v79
	v_cvt_pk_bf16_f32 v151, v151, v156
	v_lshl_add_u64 v[156:157], s[14:15], 0, v[206:207]
	v_lshl_add_u64 v[156:157], v[156:157], 0, v[190:191]
	flat_store_dwordx4 v[156:157], v[148:151]
	s_nop 1
	v_lshlrev_b32_e32 v148, 16, v152
	v_and_b32_e32 v149, 0xffff0000, v152
	v_fmac_f32_e32 v148, v88, v64
	v_fmac_f32_e32 v149, v89, v65
	v_cvt_pk_bf16_f32 v148, v148, v149
	v_lshlrev_b32_e32 v149, 16, v153
	v_and_b32_e32 v150, 0xffff0000, v153
	v_fmac_f32_e32 v149, v90, v66
	v_fmac_f32_e32 v150, v91, v67
	v_cvt_pk_bf16_f32 v149, v149, v150
	v_lshlrev_b32_e32 v150, 16, v154
	v_and_b32_e32 v151, 0xffff0000, v154
	v_fmac_f32_e32 v150, v84, v60
	v_fmac_f32_e32 v151, v85, v61
	v_cvt_pk_bf16_f32 v150, v150, v151
	v_lshlrev_b32_e32 v151, 16, v155
	v_fmac_f32_e32 v151, v86, v62
	v_and_b32_e32 v152, 0xffff0000, v155
	v_fmac_f32_e32 v152, v87, v63
	v_cvt_pk_bf16_f32 v151, v151, v152
	flat_store_dwordx4 v[156:157], v[148:151] offset:256
	s_nop 1
	v_lshlrev_b64 v[148:149], 12, v[192:193]
	v_lshl_add_u64 v[206:207], v[148:149], 0, s[12:13]
	v_lshl_add_u64 v[150:151], v[204:205], 0, v[206:207]
	flat_load_dwordx4 v[152:155], v[150:151]
	flat_load_dwordx4 v[156:159], v[150:151] offset:256
	s_mov_b64 s[12:13], 0x90000
	v_lshl_add_u64 v[208:209], v[148:149], 0, s[12:13]
	v_lshl_add_u64 v[150:151], v[204:205], 0, v[208:209]
	flat_load_dwordx4 v[160:163], v[150:151]
	flat_load_dwordx4 v[164:167], v[150:151] offset:256
	s_mov_b64 s[12:13], 0xa0000
	v_lshl_add_u64 v[210:211], v[148:149], 0, s[12:13]
	v_lshl_add_u64 v[150:151], v[204:205], 0, v[210:211]
	flat_load_dwordx4 v[168:171], v[150:151]
	flat_load_dwordx4 v[172:175], v[150:151] offset:256
	s_mov_b64 s[12:13], 0xb0000
	v_lshl_add_u64 v[214:215], v[148:149], 0, s[12:13]
	v_lshl_add_u64 v[148:149], v[204:205], 0, v[214:215]
	flat_load_dwordx4 v[176:179], v[148:149]
	s_nop 0
	flat_load_dwordx4 v[148:151], v[148:149] offset:256
	v_lshl_add_u64 v[204:205], s[14:15], 0, v[206:207]
	v_lshl_add_u64 v[204:205], v[204:205], 0, v[190:191]
	s_waitcnt vmcnt(0) lgkmcnt(0)
; __device__ __forceinline__ unsigned cvt_pk_bf16(float lo, float hi) { unsigned r; asm volatile("v_cvt_pk_bf16_f32 %0, %1, %2" : "=v"(r) : "v"(lo), "v"(hi)); return r; }
;     __device__ __forceinline__ void operator()(const f32x4 (&acc)[2][2][4][2], const Unit& u, int wr, int wc, int fr, int fq) const {
;     ...
;                 for (int m = 0; m < 4; ++m) { const size_t off = (size_t)(row0 + ai * HALF + m * 16) * ldc + col0;
; #pragma unroll
;                     for (int bj = 0; bj < 2; ++bj) { const u32x4 r = bs[m][bj]; const f32x4 a0 = acc[ai][bj][m][0], a1 = acc[ai][bj][m][1];
;                         u32x4 w;
;                         w.x = cvt_pk_bf16(__builtin_bit_cast(float, r.x << 16) + gv[bj][0][0] * a0[0], __builtin_bit_cast(float, r.x & 0xffff0000u) + gv[bj][0][1] * a0[1]);
;                         w.y = cvt_pk_bf16(__builtin_bit_cast(float, r.y << 16) + gv[bj][0][2] * a0[2], __builtin_bit_cast(float, r.y & 0xffff0000u) + gv[bj][0][3] * a0[3]);
;                         w.z = cvt_pk_bf16(__builtin_bit_cast(float, r.z << 16) + gv[bj][1][0] * a1[0], __builtin_bit_cast(float, r.z & 0xffff0000u) + gv[bj][1][1] * a1[1]);
;                         w.w = cvt_pk_bf16(__builtin_bit_cast(float, r.w << 16) + gv[bj][1][2] * a1[2], __builtin_bit_cast(float, r.w & 0xffff0000u) + gv[bj][1][3] * a1[3]);
;                         *(u32x4*)(out + off + bj * HALF) = w; } }
;                 asm volatile("" ::: "memory"); }
; template <class Epi, class Sched, bool ALIGN_EPI = false, bool SP2 = false>
; __device__ __forceinline__ void gemm_phase(PG8_LAS unsigned char* lds, const Gemm g, const Sched& S, const Epi& E) {
;     ...
;         if (!has_next) break;
; #pragma unroll
;         for (int a = 0; a < 2; ++a)
; #pragma unroll
;             for (int b = 0; b < 2; ++b)
; #pragma unroll
;                 for (int m = 0; m < 4; ++m)
; #pragma unroll
;                     for (int n = 0; n < 2; ++n) acc[a][b][m][n] = (f32x4){0.f, 0.f, 0.f, 0.f};
;         cur = nxt; cA = nA; cB = nB; ++ui;
	v_lshlrev_b32_e32 v193, 16, v152
	v_and_b32_e32 v152, 0xffff0000, v152
	v_fmac_f32_e32 v193, v72, v80
	v_fmac_f32_e32 v152, v73, v81
	v_cvt_pk_bf16_f32 v152, v193, v152
	v_lshlrev_b32_e32 v193, 16, v153
	v_and_b32_e32 v153, 0xffff0000, v153
	v_fmac_f32_e32 v193, v74, v82
	v_fmac_f32_e32 v153, v75, v83
	v_cvt_pk_bf16_f32 v153, v193, v153
	v_lshlrev_b32_e32 v193, 16, v154
	v_and_b32_e32 v154, 0xffff0000, v154
	v_fmac_f32_e32 v193, v68, v76
	v_fmac_f32_e32 v154, v69, v77
	v_cvt_pk_bf16_f32 v154, v193, v154
	v_lshlrev_b32_e32 v193, 16, v155
	v_and_b32_e32 v155, 0xffff0000, v155
	v_fmac_f32_e32 v155, v71, v79
	v_fmac_f32_e32 v193, v70, v78
	v_cvt_pk_bf16_f32 v155, v193, v155
	flat_store_dwordx4 v[204:205], v[152:155]
	s_nop 1
	v_lshlrev_b32_e32 v152, 16, v156
	v_and_b32_e32 v153, 0xffff0000, v156
	v_fmac_f32_e32 v152, v48, v64
	v_fmac_f32_e32 v153, v49, v65
	v_cvt_pk_bf16_f32 v152, v152, v153
	v_lshlrev_b32_e32 v153, 16, v157
	v_and_b32_e32 v154, 0xffff0000, v157
	v_fmac_f32_e32 v153, v50, v66
	v_fmac_f32_e32 v154, v51, v67
	v_cvt_pk_bf16_f32 v153, v153, v154
	v_lshlrev_b32_e32 v154, 16, v158
	v_and_b32_e32 v155, 0xffff0000, v158
	v_fmac_f32_e32 v154, v44, v60
	v_fmac_f32_e32 v155, v45, v61
	v_cvt_pk_bf16_f32 v154, v154, v155
	v_lshlrev_b32_e32 v155, 16, v159
	v_fmac_f32_e32 v155, v46, v62
	v_and_b32_e32 v156, 0xffff0000, v159
	v_fmac_f32_e32 v156, v47, v63
	v_cvt_pk_bf16_f32 v155, v155, v156
	flat_store_dwordx4 v[204:205], v[152:155] offset:256
	v_and_b32_e32 v156, 0xffff0000, v163
	v_fmac_f32_e32 v156, v55, v79
	v_lshlrev_b32_e32 v152, 16, v160
	v_and_b32_e32 v153, 0xffff0000, v160
	v_fmac_f32_e32 v152, v56, v80
	v_fmac_f32_e32 v153, v57, v81
	v_cvt_pk_bf16_f32 v152, v152, v153
	v_lshlrev_b32_e32 v153, 16, v161
	v_and_b32_e32 v154, 0xffff0000, v161
	v_fmac_f32_e32 v153, v58, v82
	v_fmac_f32_e32 v154, v59, v83
	v_cvt_pk_bf16_f32 v153, v153, v154
	v_lshlrev_b32_e32 v154, 16, v162
	v_and_b32_e32 v155, 0xffff0000, v162
	v_fmac_f32_e32 v154, v52, v76
	v_fmac_f32_e32 v155, v53, v77
	v_cvt_pk_bf16_f32 v154, v154, v155
	v_lshlrev_b32_e32 v155, 16, v163
	v_fmac_f32_e32 v155, v54, v78
	v_cvt_pk_bf16_f32 v155, v155, v156
	v_lshl_add_u64 v[156:157], s[14:15], 0, v[208:209]
	v_lshl_add_u64 v[156:157], v[156:157], 0, v[190:191]
	flat_store_dwordx4 v[156:157], v[152:155]
	v_and_b32_e32 v158, 0xffff0000, v167
	v_fmac_f32_e32 v158, v39, v63
	v_lshlrev_b32_e32 v152, 16, v164
	v_and_b32_e32 v153, 0xffff0000, v164
	v_fmac_f32_e32 v152, v40, v64
	v_fmac_f32_e32 v153, v41, v65
	v_cvt_pk_bf16_f32 v152, v152, v153
	v_lshlrev_b32_e32 v153, 16, v165
	v_and_b32_e32 v154, 0xffff0000, v165
	v_fmac_f32_e32 v153, v42, v66
	v_fmac_f32_e32 v154, v43, v67
	v_cvt_pk_bf16_f32 v153, v153, v154
	v_lshlrev_b32_e32 v154, 16, v166
	v_and_b32_e32 v155, 0xffff0000, v166
	v_fmac_f32_e32 v154, v36, v60
	v_fmac_f32_e32 v155, v37, v61
	v_cvt_pk_bf16_f32 v154, v154, v155
	v_lshlrev_b32_e32 v155, 16, v167
	v_fmac_f32_e32 v155, v38, v62
	v_cvt_pk_bf16_f32 v155, v155, v158
	flat_store_dwordx4 v[156:157], v[152:155] offset:256
	v_and_b32_e32 v156, 0xffff0000, v171
	v_fmac_f32_e32 v156, v31, v79
	v_lshlrev_b32_e32 v152, 16, v168
	v_and_b32_e32 v153, 0xffff0000, v168
	v_fmac_f32_e32 v152, v32, v80
	v_fmac_f32_e32 v153, v33, v81
	v_cvt_pk_bf16_f32 v152, v152, v153
	v_lshlrev_b32_e32 v153, 16, v169
	v_and_b32_e32 v154, 0xffff0000, v169
	v_fmac_f32_e32 v153, v34, v82
	v_fmac_f32_e32 v154, v35, v83
	v_cvt_pk_bf16_f32 v153, v153, v154
	v_lshlrev_b32_e32 v154, 16, v170
	v_and_b32_e32 v155, 0xffff0000, v170
	v_fmac_f32_e32 v154, v28, v76
	v_fmac_f32_e32 v155, v29, v77
	v_cvt_pk_bf16_f32 v154, v154, v155
	v_lshlrev_b32_e32 v155, 16, v171
	v_fmac_f32_e32 v155, v30, v78
	v_cvt_pk_bf16_f32 v155, v155, v156
	v_lshl_add_u64 v[156:157], s[14:15], 0, v[210:211]
	v_lshl_add_u64 v[156:157], v[156:157], 0, v[190:191]
	flat_store_dwordx4 v[156:157], v[152:155]
	v_and_b32_e32 v158, 0xffff0000, v175
	v_fmac_f32_e32 v158, v15, v63
	v_lshlrev_b32_e32 v152, 16, v172
	v_and_b32_e32 v153, 0xffff0000, v172
	v_fmac_f32_e32 v152, v16, v64
	v_fmac_f32_e32 v153, v17, v65
	v_cvt_pk_bf16_f32 v152, v152, v153
	v_lshlrev_b32_e32 v153, 16, v173
	v_and_b32_e32 v154, 0xffff0000, v173
	v_fmac_f32_e32 v153, v18, v66
	v_fmac_f32_e32 v154, v19, v67
	v_cvt_pk_bf16_f32 v153, v153, v154
	v_lshlrev_b32_e32 v154, 16, v174
	v_and_b32_e32 v155, 0xffff0000, v174
	v_fmac_f32_e32 v154, v12, v60
	v_fmac_f32_e32 v155, v13, v61
	v_cvt_pk_bf16_f32 v154, v154, v155
	v_lshlrev_b32_e32 v155, 16, v175
	v_fmac_f32_e32 v155, v14, v62
	v_cvt_pk_bf16_f32 v155, v155, v158
	flat_store_dwordx4 v[156:157], v[152:155] offset:256
	v_and_b32_e32 v156, 0xffff0000, v179
	v_fmac_f32_e32 v156, v23, v79
	v_lshlrev_b32_e32 v152, 16, v176
	v_and_b32_e32 v153, 0xffff0000, v176
	v_fmac_f32_e32 v152, v24, v80
	v_fmac_f32_e32 v153, v25, v81
	v_cvt_pk_bf16_f32 v152, v152, v153
	v_lshlrev_b32_e32 v153, 16, v177
	v_and_b32_e32 v154, 0xffff0000, v177
	v_fmac_f32_e32 v153, v26, v82
	v_fmac_f32_e32 v154, v27, v83
	v_cvt_pk_bf16_f32 v153, v153, v154
	v_lshlrev_b32_e32 v154, 16, v178
	v_and_b32_e32 v155, 0xffff0000, v178
	v_fmac_f32_e32 v154, v20, v76
	v_fmac_f32_e32 v155, v21, v77
	v_cvt_pk_bf16_f32 v154, v154, v155
	v_lshlrev_b32_e32 v155, 16, v179
	v_fmac_f32_e32 v155, v22, v78
	v_cvt_pk_bf16_f32 v155, v155, v156
	v_lshl_add_u64 v[156:157], s[14:15], 0, v[214:215]
	v_lshl_add_u64 v[156:157], v[156:157], 0, v[190:191]
	flat_store_dwordx4 v[156:157], v[152:155]
	s_nop 1
	v_lshlrev_b32_e32 v152, 16, v148
	v_and_b32_e32 v148, 0xffff0000, v148
	v_fmac_f32_e32 v152, v8, v64
	v_fmac_f32_e32 v148, v9, v65
	v_cvt_pk_bf16_f32 v148, v152, v148
	v_lshlrev_b32_e32 v152, 16, v149
	v_and_b32_e32 v149, 0xffff0000, v149
	v_fmac_f32_e32 v152, v10, v66
	v_fmac_f32_e32 v149, v11, v67
	v_cvt_pk_bf16_f32 v149, v152, v149
	v_lshlrev_b32_e32 v152, 16, v150
	v_and_b32_e32 v150, 0xffff0000, v150
	v_fmac_f32_e32 v152, v4, v60
	v_fmac_f32_e32 v150, v5, v61
	v_cvt_pk_bf16_f32 v150, v152, v150
	v_lshlrev_b32_e32 v152, 16, v151
	v_and_b32_e32 v151, 0xffff0000, v151
	v_fmac_f32_e32 v151, v7, v63
	v_fmac_f32_e32 v152, v6, v62
	v_cvt_pk_bf16_f32 v151, v152, v151
	flat_store_dwordx4 v[156:157], v[148:151] offset:256
	s_cbranch_execnz .LBB0_2038
	s_branch .LBB0_2050
